# P4 up-proj epilogue: per-row RMS factor computed once per row panel and cached in 8 VGPRs across the 4 tiles of that panel (removes part loads + reduction + divisions from 6 of 8 epilogues)
# speedup vs baseline: 1.0151x; 1.0151x over previous
; #define PG8_WAIT_V(n) asm volatile("s_waitcnt vmcnt(" #n ")" ::: "memory")
; #define PG8_BAR __builtin_amdgcn_s_barrier()
; template <class Epi, class Sched, bool ALIGN_EPI = false, bool SP2 = false, bool ABLK = false>
; __device__ __forceinline__ void gemm_phase(PG8_LAS unsigned char* lds, const Gemm g, const Sched& S, const Epi& E) {
;     ...
;     for (int i = 0; i < 2; ++i) { int R, C; stage_rc(tid * 16 + i * 8192, R, C); const int Rb = Epi::PERM ? ((R & ~31) + perm32(R & 31)) : R;
;         voffA[i] = (unsigned)(R * (ABLK ? BK : K) + C) * 2u; voffB[i] = (unsigned)(Rb * K + C) * 2u; }
;     const size_t kstep = (size_t)(BK * 2);
;     const size_t hstep = (size_t)HALF * K * 2;
;     const size_t tstep = 2 * hstep;
;     const size_t kstepA = ABLK ? (size_t)(BM * BK * 2) : kstep, hstepA = ABLK ? (size_t)(HALF * BK * 2) : hstep, tstepA = ABLK ? (size_t)nt * (BM * BK * 2) : tstep;
;     const unsigned ldsw = (unsigned)wid * 1024u;
;     const int aoff = lds_byte(wr * 64 + fr, fq * 8), boff = lds_byte(wc * 32 + fr, fq * 8);
;     ...
;     Unit cur, nxt; int ui = 0;
;     if (!S.next(0, cur)) return;
;     f32x4 acc[2][2][4][2];
; #pragma unroll
;     for (int a = 0; a < 2; ++a)
; #pragma unroll
;         for (int b = 0; b < 2; ++b)
; #pragma unroll
;             for (int m = 0; m < 4; ++m)
; #pragma unroll
;                 for (int n = 0; n < 2; ++n) acc[a][b][m][n] = (f32x4){0.f, 0.f, 0.f, 0.f};
;     bf16x8 At[4][2], B0[2][2], B1[2][2];
;     const char* cA = (const char*)g.A + (size_t)cur.pm * tstepA; const char* cB = (const char*)g.Bt + (size_t)cur.pn * tstep;
;     S.a_ready(cur);
;     if constexpr (SP2) {
;         PG8_STAGE(PG8_SB(0, 0), cB, voffB); PG8_STAGE(PG8_SB(0, 1), cB + hstep, voffB); PG8_STAGE(PG8_SA(0, 0), cA, voffA); PG8_STAGE(PG8_SA(0, 1), cA + hstepA, voffA);
;         if (wr == 1) PG8_BAR;
;         PG8_WAIT_V(2); PG8_BAR;
;         PG8_STAGE(PG8_SB(1, 0), cB + kstep, voffB); PG8_STAGE(PG8_SA(1, 0), cA + kstepA, voffA); PG8_STAGE(PG8_SB(1, 1), cB + hstep + kstep, voffB);
;         PG8_WAIT_V(6); PG8_BAR;
;     } else {
;         PG8_STAGE(PG8_SB(0, 0), cB, voffB); PG8_STAGE(PG8_SA(0, 0), cA, voffA); PG8_STAGE(PG8_SB(0, 1), cB + hstep, voffB); PG8_STAGE(PG8_SA(0, 1), cA + hstepA, voffA);
;         if (wr == 1) PG8_BAR;
;         PG8_WAIT_V(4); PG8_BAR;
.LBB0_525:
	s_or_b64 exec, exec, s[6:7]
	s_add_u32 s42, s70, 0x6000000
	s_addc_u32 s43, s71, 0
	v_mov_b32_e32 v7, v175
	s_barrier
	s_cmpk_gt_i32 s69, 0xff
	v_readfirstlane_b32 s18, v7
	s_cbranch_scc1 .LBB0_541
	v_lshlrev_b32_e32 v0, 4, v7
	v_add_u32_e32 v1, 0x2000, v0
	v_ashrrev_i32_e32 v2, 31, v1
	v_lshrrev_b32_e32 v2, 22, v2
	v_add_u32_e32 v2, v1, v2
	v_ashrrev_i32_e32 v4, 10, v2
	v_mul_i32_i24_e32 v2, 0x400, v4
	v_sub_u32_e32 v1, v1, v2
	v_lshrrev_b32_e32 v2, 4, v1
	v_bitop3_b32 v1, v2, v1, 32 bitop3:0x6c
	v_ashrrev_i32_e32 v2, 31, v1
	v_lshrrev_b32_e32 v2, 26, v2
	v_add_u32_e32 v2, v1, v2
	v_lshlrev_b32_e32 v3, 3, v4
	v_ashrrev_i32_e32 v5, 6, v2
	v_and_b32_e32 v3, -16, v3
	v_add_u32_e32 v3, v5, v3
	v_and_b32_e32 v6, 3, v5
	s_mov_b32 s2, 0x1fffe0
	v_lshrrev_b32_e32 v8, 2, v3
	v_lshlrev_b32_e32 v9, 1, v3
	v_and_b32_e32 v2, 0xc0, v2
	v_and_or_b32 v6, v3, s2, v6
	v_and_b32_e32 v8, 4, v8
	v_and_b32_e32 v9, 24, v9
	v_sub_u32_e32 v1, v1, v2
	v_mov_b32_e32 v2, 1
	v_or3_b32 v8, v6, v8, v9
	v_lshlrev_b32_e32 v6, 5, v4
	v_ashrrev_i16_sdwa v1, v2, sext(v1) dst_sel:DWORD dst_unused:UNUSED_PAD src0_sel:DWORD src1_sel:BYTE_0
	v_and_b32_e32 v9, 32, v6
	v_bfe_i32 v6, v1, 0, 16
	v_add_lshl_u32 v1, v9, v6, 1
	v_lshl_add_u32 v132, v8, 11, v1
	v_lshl_add_u32 v134, v3, 7, v1
	v_bfe_i32 v1, v7, 27, 1
	v_lshrrev_b32_e32 v1, 22, v1
	v_add_u32_e32 v1, v0, v1
	v_and_b32_e32 v1, 0xfffffc00, v1
	v_sub_u32_e32 v0, v0, v1
	v_lshrrev_b32_e32 v1, 4, v0
	v_ashrrev_i32_e32 v3, 31, v7
	v_bitop3_b32 v0, v1, v0, 32 bitop3:0x6c
	v_lshrrev_b32_e32 v3, 26, v3
	v_ashrrev_i32_e32 v1, 31, v0
	v_add_u32_e32 v3, v7, v3
	v_lshrrev_b32_e32 v1, 26, v1
	v_ashrrev_i32_e32 v9, 6, v3
	v_add_u32_e32 v1, v0, v1
	v_lshlrev_b32_e32 v3, 3, v9
	v_ashrrev_i32_e32 v8, 6, v1
	v_and_b32_e32 v3, -16, v3
	v_add_u32_e32 v3, v8, v3
	v_and_b32_e32 v10, 3, v8
	v_and_or_b32 v10, v3, s2, v10
	s_ashr_i32 s2, s69, 31
	s_lshr_b32 s2, s2, 25
	s_add_i32 s2, s69, s2
	v_readlane_b32 s7, v244, 2
	s_ashr_i32 s6, s2, 7
	s_and_b32 s2, s2, 0xffffff80
	s_bfe_u32 s7, s7, 0x30003
	s_sub_i32 s2, s69, s2
	s_lshl_b32 s6, s6, 3
	s_or_b32 s7, s46, s7
	v_lshrrev_b32_e32 v11, 2, v3
	v_lshlrev_b32_e32 v12, 1, v3
	v_and_b32_e32 v1, 0xc0, v1
	s_add_i32 s30, s7, s6
	s_ashr_i32 s6, s2, 3
	s_ashr_i32 s16, s18, 6
	v_and_b32_e32 v11, 4, v11
	v_and_b32_e32 v12, 24, v12
	v_sub_u32_e32 v0, v0, v1
	s_ashr_i32 s31, s30, 31
	s_ashr_i32 s7, s6, 31
	s_ashr_i32 s19, s18, 8
	s_lshl_b32 s3, s16, 10
	v_or3_b32 v11, v10, v11, v12
	v_lshlrev_b32_e32 v10, 5, v9
	v_ashrrev_i16_sdwa v0, v2, sext(v0) dst_sel:DWORD dst_unused:UNUSED_PAD src0_sel:DWORD src1_sel:BYTE_0
	s_lshl_b64 s[14:15], s[30:31], 19
	s_lshl_b64 s[20:21], s[6:7], 19
	v_and_b32_e32 v12, 32, v10
	v_bfe_i32 v10, v0, 0, 16
	s_add_u32 s34, s52, s20
	v_add_lshl_u32 v0, v12, v10, 1
	s_addc_u32 s35, s53, s21
	s_add_i32 s40, s3, 0
	v_lshl_add_u32 v136, v11, 11, v0
	s_add_i32 m0, s40, 0x10000
	v_lshl_add_u32 v138, v3, 7, v0
	global_load_lds_dwordx4 v136, s[34:35]
	s_add_i32 m0, s40, 0x12000
	s_add_u32 s20, s34, 0x40000
	global_load_lds_dwordx4 v132, s[34:35]
	s_addc_u32 s21, s35, 0
	s_add_i32 m0, s40, 0x14000
	v_mov_b32_e32 v141, 0
	global_load_lds_dwordx4 v136, s[20:21]
	s_add_i32 m0, s40, 0x16000
	s_add_u32 s36, s10, s14
	s_addc_u32 s37, s11, s15
	s_add_i32 s41, s40, 0x2000
	global_load_lds_dwordx4 v132, s[20:21]
	s_mov_b32 m0, s40
	s_add_u32 s14, s36, 0x4000
	global_load_lds_dwordx4 v138, s[36:37]
	s_mov_b32 m0, s41
	s_addc_u32 s15, s37, 0
	s_add_i32 s44, s40, 0x4000
	global_load_lds_dwordx4 v134, s[36:37]
	s_mov_b32 m0, s44
	s_add_i32 s45, s40, 0x6000
	global_load_lds_dwordx4 v138, s[14:15]
	s_mov_b32 m0, s45
	v_mov_b32_e32 v137, v141
	global_load_lds_dwordx4 v134, s[14:15]
	v_mov_b32_e32 v133, v141
	s_cmp_eq_u32 s19, 1
	s_movk_i32 s47, 0x2000
	s_mov_b32 s48, 0
	s_mov_b32 s100, -1
	s_mov_b32 s49, 0x10000
	v_lshl_add_u64 v[2:3], s[34:35], 0, v[136:137]
	v_lshl_add_u64 v[0:1], s[34:35], 0, v[132:133]
	v_mov_b32_e32 v139, v141
	v_mov_b32_e32 v135, v141
	s_cselect_b64 s[14:15], -1, 0
	s_cmp_lg_u32 s19, 1
	s_mov_b64 s[20:21], 0x4000
	s_cbranch_scc1 .LBB0_528
	s_barrier

;     __device__ __forceinline__ void operator()(const f32x4 (&acc)[2][2][4][2], const Unit& u, int wr, int wc, int fr, int fq) const {
;     ...
;             for (int m = 0; m < 4; ++m) pv[ai][m] = __builtin_nontemporal_load((const f32x4*)(part + (size_t)(row0 + ai * HALF + m * 16) * 16 + 4 * fq));
;         float r2[2][4];
; #pragma unroll
;         for (int ai = 0; ai < 2; ++ai)
; #pragma unroll
;             for (int m = 0; m < 4; ++m) { float s = (pv[ai][m][0] + pv[ai][m][1]) + (pv[ai][m][2] + pv[ai][m][3]); s += __shfl_xor(s, 16); s += __shfl_xor(s, 32); r2[ai][m] = 1.0f / (s * (1.0f / 1024.0f) + eps); }
.LBB0_537:
	s_cmp_eq_u32 s30, s100
	s_cbranch_scc1 .Lp4_r2_cached
	s_mov_b32 s100, s30
	v_lshl_add_u32 v204, s30, 8, v142
	v_mov_b32_e32 v205, 0
	v_lshlrev_b64 v[206:207], 6, v[204:205]
	v_xor_b32_e32 v240, 16, v169
	v_lshl_add_u64 v[206:207], v[160:161], 0, v[206:207]
	v_xor_b32_e32 v241, 32, v169
	global_load_dwordx4 v[208:211], v[206:207], off nt
	global_load_dwordx4 v[212:215], v[206:207], off offset:1024 nt
	global_load_dwordx4 v[216:219], v[206:207], off offset:2048 nt
	global_load_dwordx4 v[220:223], v[206:207], off offset:3072 nt
	v_add_co_u32_e32 v242, vcc, 0x2000, v206
	v_lshlrev_b32_e32 v240, 2, v240
	s_nop 0
	v_addc_co_u32_e32 v243, vcc, 0, v207, vcc
	v_lshlrev_b32_e32 v241, 2, v241
	global_load_dwordx4 v[224:227], v[242:243], off nt
	global_load_dwordx4 v[228:231], v[242:243], off offset:1024 nt
	global_load_dwordx4 v[232:235], v[242:243], off offset:2048 nt
	global_load_dwordx4 v[236:239], v[242:243], off offset:3072 nt
	s_waitcnt vmcnt(0)
	v_add_f32_e32 v208, v208, v209
	v_add_f32_e32 v210, v210, v211
	v_add_f32_e32 v212, v212, v213
	v_add_f32_e32 v214, v214, v215
	v_add_f32_e32 v216, v216, v217
	v_add_f32_e32 v218, v218, v219
	v_add_f32_e32 v220, v220, v221
	v_add_f32_e32 v222, v222, v223
	v_add_f32_e32 v224, v224, v225
	v_add_f32_e32 v226, v226, v227
	v_add_f32_e32 v228, v228, v229
	v_add_f32_e32 v230, v230, v231
	v_add_f32_e32 v232, v232, v233
	v_add_f32_e32 v234, v234, v235
	v_add_f32_e32 v236, v236, v237
	v_add_f32_e32 v238, v238, v239
	v_add_f32_e32 v208, v208, v210
	v_add_f32_e32 v212, v212, v214
	v_add_f32_e32 v216, v216, v218
	v_add_f32_e32 v220, v220, v222
	v_add_f32_e32 v224, v224, v226
	v_add_f32_e32 v228, v228, v230
	v_add_f32_e32 v232, v232, v234
	v_add_f32_e32 v236, v236, v238
	ds_bpermute_b32 v209, v240, v208
	ds_bpermute_b32 v213, v240, v212
	ds_bpermute_b32 v217, v240, v216
	ds_bpermute_b32 v221, v240, v220
	ds_bpermute_b32 v225, v240, v224
	ds_bpermute_b32 v229, v240, v228
	ds_bpermute_b32 v233, v240, v232
	ds_bpermute_b32 v237, v240, v236
	s_waitcnt lgkmcnt(0)
	v_add_f32_e32 v208, v208, v209
	v_add_f32_e32 v212, v212, v213
	v_add_f32_e32 v216, v216, v217
	v_add_f32_e32 v220, v220, v221
	v_add_f32_e32 v224, v224, v225
	v_add_f32_e32 v228, v228, v229
	v_add_f32_e32 v232, v232, v233
	v_add_f32_e32 v236, v236, v237
	ds_bpermute_b32 v209, v241, v208
	ds_bpermute_b32 v213, v241, v212
	ds_bpermute_b32 v217, v241, v216
	ds_bpermute_b32 v221, v241, v220
	ds_bpermute_b32 v225, v241, v224
	ds_bpermute_b32 v229, v241, v228
	ds_bpermute_b32 v233, v241, v232
	ds_bpermute_b32 v237, v241, v236
	s_waitcnt lgkmcnt(0)
	v_add_f32_e32 v208, v208, v209
	v_add_f32_e32 v212, v212, v213
	v_add_f32_e32 v216, v216, v217
	v_add_f32_e32 v220, v220, v221
	v_add_f32_e32 v224, v224, v225
	v_add_f32_e32 v228, v228, v229
	v_add_f32_e32 v232, v232, v233
	v_add_f32_e32 v236, v236, v237
	v_fmamk_f32 v208, v208, 0x3a800000, v170
	v_fmamk_f32 v212, v212, 0x3a800000, v170
	v_fmamk_f32 v216, v216, 0x3a800000, v170
	v_fmamk_f32 v220, v220, 0x3a800000, v170
	v_fmamk_f32 v224, v224, 0x3a800000, v170
	v_fmamk_f32 v228, v228, 0x3a800000, v170
	v_fmamk_f32 v232, v232, 0x3a800000, v170
	v_fmamk_f32 v236, v236, 0x3a800000, v170
	v_div_scale_f32 v209, vcc, v208, v208, 1.0
	v_rcp_f32_e32 v210, v209
	v_div_scale_f32 v211, vcc, 1.0, v208, 1.0
	v_fma_f32 v240, -v209, v210, 1.0
	v_fmac_f32_e32 v210, v240, v210
	v_mul_f32_e32 v241, v211, v210
	v_fma_f32 v240, -v209, v241, v211
	v_fmac_f32_e32 v241, v240, v210
	v_fma_f32 v240, -v209, v241, v211
	v_div_fmas_f32 v240, v240, v210, v241
	v_div_fixup_f32 v245, v240, v208, 1.0
	v_div_scale_f32 v213, vcc, v212, v212, 1.0
	v_rcp_f32_e32 v214, v213
	v_div_scale_f32 v215, vcc, 1.0, v212, 1.0
	v_fma_f32 v240, -v213, v214, 1.0
	v_fmac_f32_e32 v214, v240, v214
	v_mul_f32_e32 v241, v215, v214
	v_fma_f32 v240, -v213, v241, v215
	v_fmac_f32_e32 v241, v240, v214
	v_fma_f32 v240, -v213, v241, v215
	v_div_fmas_f32 v240, v240, v214, v241
	v_div_fixup_f32 v246, v240, v212, 1.0
	v_div_scale_f32 v217, vcc, v216, v216, 1.0
	v_rcp_f32_e32 v218, v217
	v_div_scale_f32 v219, vcc, 1.0, v216, 1.0
	v_fma_f32 v240, -v217, v218, 1.0
	v_fmac_f32_e32 v218, v240, v218
	v_mul_f32_e32 v241, v219, v218
	v_fma_f32 v240, -v217, v241, v219
	v_fmac_f32_e32 v241, v240, v218
	v_fma_f32 v240, -v217, v241, v219
	v_div_fmas_f32 v240, v240, v218, v241
	v_div_fixup_f32 v247, v240, v216, 1.0
	v_div_scale_f32 v221, vcc, v220, v220, 1.0
	v_rcp_f32_e32 v222, v221
	v_div_scale_f32 v223, vcc, 1.0, v220, 1.0
	v_fma_f32 v240, -v221, v222, 1.0
	v_fmac_f32_e32 v222, v240, v222
	v_mul_f32_e32 v241, v223, v222
	v_fma_f32 v240, -v221, v241, v223
	v_fmac_f32_e32 v241, v240, v222
	v_fma_f32 v240, -v221, v241, v223
	v_div_fmas_f32 v240, v240, v222, v241
	v_div_fixup_f32 v248, v240, v220, 1.0
	v_div_scale_f32 v225, vcc, v224, v224, 1.0
	v_rcp_f32_e32 v226, v225
	v_div_scale_f32 v227, vcc, 1.0, v224, 1.0
	v_fma_f32 v240, -v225, v226, 1.0
	v_fmac_f32_e32 v226, v240, v226
	v_mul_f32_e32 v241, v227, v226
	v_fma_f32 v240, -v225, v241, v227
	v_fmac_f32_e32 v241, v240, v226
	v_fma_f32 v240, -v225, v241, v227
	v_div_fmas_f32 v240, v240, v226, v241
	v_div_fixup_f32 v249, v240, v224, 1.0
	v_div_scale_f32 v229, vcc, v228, v228, 1.0
	v_rcp_f32_e32 v230, v229
	v_div_scale_f32 v231, vcc, 1.0, v228, 1.0
	v_fma_f32 v240, -v229, v230, 1.0
	v_fmac_f32_e32 v230, v240, v230
	v_mul_f32_e32 v241, v231, v230
	v_fma_f32 v240, -v229, v241, v231
	v_fmac_f32_e32 v241, v240, v230
	v_fma_f32 v240, -v229, v241, v231
	v_div_fmas_f32 v240, v240, v230, v241
	v_div_fixup_f32 v250, v240, v228, 1.0
	v_div_scale_f32 v233, vcc, v232, v232, 1.0
	v_rcp_f32_e32 v234, v233
	v_div_scale_f32 v235, vcc, 1.0, v232, 1.0
	v_fma_f32 v240, -v233, v234, 1.0
	v_fmac_f32_e32 v234, v240, v234
	v_mul_f32_e32 v241, v235, v234
	v_fma_f32 v240, -v233, v241, v235
	v_fmac_f32_e32 v241, v240, v234
	v_fma_f32 v240, -v233, v241, v235
	v_div_fmas_f32 v240, v240, v234, v241
	v_div_fixup_f32 v251, v240, v232, 1.0
	v_div_scale_f32 v237, vcc, v236, v236, 1.0
	v_rcp_f32_e32 v238, v237
	v_div_scale_f32 v239, vcc, 1.0, v236, 1.0
	v_fma_f32 v240, -v237, v238, 1.0
	v_fmac_f32_e32 v238, v240, v238
	v_mul_f32_e32 v241, v239, v238
	v_fma_f32 v240, -v237, v241, v239
	v_fmac_f32_e32 v241, v240, v238
	v_fma_f32 v240, -v237, v241, v239
	v_div_fmas_f32 v240, v240, v238, v241
	v_div_fixup_f32 v252, v240, v236, 1.0
; __device__ __forceinline__ unsigned cvt_pk_bf16(float lo, float hi) { unsigned r; asm volatile("v_cvt_pk_bf16_f32 %0, %1, %2" : "=v"(r) : "v"(lo), "v"(hi)); return r; }
;     __device__ __forceinline__ void operator()(const f32x4 (&acc)[2][2][4][2], const Unit& u, int wr, int wc, int fr, int fq) const {
;     ...
;             for (int m = 0; m < 4; ++m) { const int row = row0 + ai * HALF + m * 16; const float rr = r2[ai][m];
;                 bf16_t* rowp = O + ((size_t)u.pm * (ldc / 64) * 256 + (size_t)(row - u.pm * BM)) * 64 + (size_t)(col0 >> 6) * (256 * 64) + (col0 & 63);
; #pragma unroll
;                 for (int bj = 0; bj < 2; ++bj) { f32x4 v0 = acc[ai][bj][m][0], v1 = acc[ai][bj][m][1];
; #pragma unroll
;                     for (int e = 0; e < 4; ++e) { const float a = fmaxf(v0[e], 0.f), b = fmaxf(v1[e], 0.f); v0[e] = a * a * rr; v1[e] = b * b * rr; }
;                     u32x4 w; w.x = cvt_pk_bf16(v0[0], v0[1]); w.y = cvt_pk_bf16(v0[2], v0[3]); w.z = cvt_pk_bf16(v1[0], v1[1]); w.w = cvt_pk_bf16(v1[2], v1[3]);
;                     *(u32x4*)(rowp + (size_t)bj * (2 * 256 * 64)) = w; } }
.Lp4_r2_cached:
	s_lshl_b32 s2, s6, 8
	s_or_b32 s21, s2, s54
	v_max_f32_e32 v120, v120, v120
	s_nop 0
	s_nop 0
	s_ashr_i32 s31, s30, 31
	v_max_f32_e32 v120, 0, v120
	v_max_f32_e32 v121, v121, v121
	v_max_f32_e32 v122, v122, v122
	v_mul_f32_e32 v120, v120, v120
	v_max_f32_e32 v121, 0, v121
	v_max_f32_e32 v122, 0, v122
	v_mul_f32_e32 v121, v121, v121
	v_mul_f32_e32 v122, v122, v122
	v_max_f32_e32 v124, v124, v124
	v_max_f32_e32 v123, v123, v123
	v_max_f32_e32 v124, 0, v124
	v_max_f32_e32 v123, 0, v123
	v_max_f32_e32 v112, v112, v112
	v_mul_f32_e32 v124, v124, v124
	v_mul_f32_e32 v123, v123, v123
	v_max_f32_e32 v112, 0, v112
	v_max_f32_e32 v113, v113, v113
	v_max_f32_e32 v114, v114, v114
	v_mul_f32_e32 v112, v112, v112
	v_max_f32_e32 v113, 0, v113
	v_max_f32_e32 v114, 0, v114
	v_max_f32_e32 v116, v116, v116
	v_mul_f32_e32 v113, v113, v113
	v_mul_f32_e32 v114, v114, v114
	v_max_f32_e32 v116, 0, v116
	v_mul_f32_e32 v116, v116, v116
	v_max_f32_e32 v115, v115, v115
	v_max_f32_e32 v115, 0, v115
	v_max_f32_e32 v104, v104, v104
	v_mul_f32_e32 v115, v115, v115
	v_max_f32_e32 v104, 0, v104
	v_max_f32_e32 v105, v105, v105
	v_max_f32_e32 v106, v106, v106
	v_mul_f32_e32 v104, v104, v104
	v_max_f32_e32 v105, 0, v105
	v_max_f32_e32 v106, 0, v106
	v_mul_f32_e32 v105, v105, v105
	v_mul_f32_e32 v106, v106, v106
	v_max_f32_e32 v108, v108, v108
	v_max_f32_e32 v107, v107, v107
	v_max_f32_e32 v108, 0, v108
	v_max_f32_e32 v107, 0, v107
	v_max_f32_e32 v96, v96, v96
	v_mul_f32_e32 v108, v108, v108
	v_mul_f32_e32 v107, v107, v107
	v_max_f32_e32 v96, 0, v96
	v_max_f32_e32 v97, v97, v97
	v_max_f32_e32 v98, v98, v98
	v_mul_f32_e32 v96, v96, v96
	s_lshl_b64 s[8:9], s[30:31], 21
	v_mul_f32_e32 v124, v124, v245
	s_ashr_i32 s6, s21, 6
	s_ashr_i32 s7, s6, 31
	s_lshl_b64 s[6:7], s[6:7], 15
	s_add_u32 s8, s42, s8
	v_mul_f32_e32 v173, v120, v245
	v_max_f32_e32 v120, v125, v125
	s_addc_u32 s9, s43, s9
	v_max_f32_e32 v120, 0, v120
	v_mul_f32_e32 v125, v121, v245
	v_max_f32_e32 v121, v126, v126
	v_mul_f32_e32 v126, v122, v245
	v_max_f32_e32 v122, v127, v127
	v_lshl_add_u64 v[130:131], s[8:9], 0, v[144:145]
	v_mul_f32_e32 v120, v120, v120
	v_max_f32_e32 v121, 0, v121
	v_max_f32_e32 v122, 0, v122
	v_lshl_add_u64 v[130:131], v[130:131], 0, s[6:7]
	v_mul_f32_e32 v120, v120, v245
	v_mul_f32_e32 v121, v121, v121
	v_mul_f32_e32 v122, v122, v122
	v_lshl_add_u64 v[130:131], v[130:131], 0, v[140:141]
	v_mul_f32_e32 v121, v121, v245
	v_mul_f32_e32 v122, v122, v245
	v_mul_f32_e32 v123, v123, v245
	v_cvt_pk_bf16_f32 v120, v124, v120
	v_cvt_pk_bf16_f32 v121, v121, v122
	v_cvt_pk_bf16_f32 v122, v173, v125
	v_cvt_pk_bf16_f32 v123, v126, v123
	global_store_dwordx4 v[130:131], v[120:123], off
	v_mul_f32_e32 v116, v116, v245
	v_mul_f32_e32 v115, v115, v245
	v_mul_f32_e32 v120, v112, v245
	v_max_f32_e32 v112, v117, v117
	v_max_f32_e32 v112, 0, v112
	v_mul_f32_e32 v117, v113, v245
	v_max_f32_e32 v113, v118, v118
	v_mul_f32_e32 v118, v114, v245
	v_max_f32_e32 v114, v119, v119
	v_mul_f32_e32 v112, v112, v112
	v_max_f32_e32 v113, 0, v113
	v_max_f32_e32 v114, 0, v114
	v_mul_f32_e32 v112, v112, v245
	v_mul_f32_e32 v113, v113, v113
	v_mul_f32_e32 v114, v114, v114
	v_mul_f32_e32 v113, v113, v245
	v_mul_f32_e32 v114, v114, v245
	v_cvt_pk_bf16_f32 v112, v116, v112
	v_add_co_u32_e32 v116, vcc, s49, v130
	v_cvt_pk_bf16_f32 v113, v113, v114
	v_cvt_pk_bf16_f32 v114, v120, v117
	v_cvt_pk_bf16_f32 v115, v118, v115
	v_mul_f32_e32 v108, v108, v246
	s_nop 0
	v_addc_co_u32_e32 v117, vcc, 0, v131, vcc
	global_store_dwordx4 v[116:117], v[112:115], off
	v_mul_f32_e32 v107, v107, v246
	v_max_f32_e32 v97, 0, v97
	v_mul_f32_e32 v114, v104, v246
	v_max_f32_e32 v104, v109, v109
	v_max_f32_e32 v104, 0, v104
	v_mul_f32_e32 v109, v105, v246
	v_max_f32_e32 v105, v110, v110
	v_mul_f32_e32 v110, v106, v246
	v_max_f32_e32 v106, v111, v111
	v_lshl_add_u64 v[112:113], s[8:9], 0, v[146:147]
	v_mul_f32_e32 v104, v104, v104
	v_max_f32_e32 v105, 0, v105
	v_max_f32_e32 v106, 0, v106
	v_lshl_add_u64 v[112:113], v[112:113], 0, s[6:7]
	v_mul_f32_e32 v104, v104, v246
	v_mul_f32_e32 v105, v105, v105
	v_mul_f32_e32 v106, v106, v106
	v_lshl_add_u64 v[112:113], v[112:113], 0, v[140:141]
	v_mul_f32_e32 v105, v105, v246
	v_mul_f32_e32 v106, v106, v246
	v_cvt_pk_bf16_f32 v104, v108, v104
	v_max_f32_e32 v98, 0, v98
	v_cvt_pk_bf16_f32 v105, v105, v106
	v_cvt_pk_bf16_f32 v106, v114, v109
	v_cvt_pk_bf16_f32 v107, v110, v107
	global_store_dwordx4 v[112:113], v[104:107], off
	v_max_f32_e32 v100, v100, v100
	v_mul_f32_e32 v97, v97, v97
	v_mul_f32_e32 v104, v96, v246
	v_max_f32_e32 v96, v101, v101
	v_mul_f32_e32 v98, v98, v98
	v_max_f32_e32 v100, 0, v100
	v_max_f32_e32 v96, 0, v96
	v_mul_f32_e32 v101, v97, v246
	v_max_f32_e32 v97, v102, v102
	v_mul_f32_e32 v102, v98, v246
	v_max_f32_e32 v98, v103, v103
	v_mul_f32_e32 v100, v100, v100
	v_mul_f32_e32 v96, v96, v96
	v_max_f32_e32 v97, 0, v97
	v_max_f32_e32 v98, 0, v98
	v_max_f32_e32 v99, v99, v99
	v_mul_f32_e32 v100, v100, v246
	v_mul_f32_e32 v96, v96, v246
	v_mul_f32_e32 v97, v97, v97
	v_max_f32_e32 v99, 0, v99
	v_mul_f32_e32 v98, v98, v98
	v_max_f32_e32 v88, v88, v88
	v_mul_f32_e32 v97, v97, v246
	v_mul_f32_e32 v98, v98, v246
	v_mul_f32_e32 v99, v99, v99
	v_cvt_pk_bf16_f32 v96, v100, v96
	v_add_co_u32_e32 v100, vcc, s49, v112
	v_max_f32_e32 v88, 0, v88
	v_max_f32_e32 v89, v89, v89
	v_max_f32_e32 v90, v90, v90
	v_mul_f32_e32 v99, v99, v246
	v_cvt_pk_bf16_f32 v97, v97, v98
	v_cvt_pk_bf16_f32 v98, v104, v101
	v_addc_co_u32_e32 v101, vcc, 0, v113, vcc
	v_mul_f32_e32 v88, v88, v88
	v_max_f32_e32 v89, 0, v89
	v_max_f32_e32 v90, 0, v90
	v_cvt_pk_bf16_f32 v99, v102, v99
	global_store_dwordx4 v[100:101], v[96:99], off
; __device__ __forceinline__ unsigned cvt_pk_bf16(float lo, float hi) { unsigned r; asm volatile("v_cvt_pk_bf16_f32 %0, %1, %2" : "=v"(r) : "v"(lo), "v"(hi)); return r; }
;     __device__ __forceinline__ void operator()(const f32x4 (&acc)[2][2][4][2], const Unit& u, int wr, int wc, int fr, int fq) const {
;     ...
;             for (int m = 0; m < 4; ++m) { const int row = row0 + ai * HALF + m * 16; const float rr = r2[ai][m];
;                 bf16_t* rowp = O + ((size_t)u.pm * (ldc / 64) * 256 + (size_t)(row - u.pm * BM)) * 64 + (size_t)(col0 >> 6) * (256 * 64) + (col0 & 63);
; #pragma unroll
;                 for (int bj = 0; bj < 2; ++bj) { f32x4 v0 = acc[ai][bj][m][0], v1 = acc[ai][bj][m][1];
; #pragma unroll
;                     for (int e = 0; e < 4; ++e) { const float a = fmaxf(v0[e], 0.f), b = fmaxf(v1[e], 0.f); v0[e] = a * a * rr; v1[e] = b * b * rr; }
;                     u32x4 w; w.x = cvt_pk_bf16(v0[0], v0[1]); w.y = cvt_pk_bf16(v0[2], v0[3]); w.z = cvt_pk_bf16(v1[0], v1[1]); w.w = cvt_pk_bf16(v1[2], v1[3]);
;                     *(u32x4*)(rowp + (size_t)bj * (2 * 256 * 64)) = w; } }
	v_mul_f32_e32 v89, v89, v89
	v_mul_f32_e32 v90, v90, v90
	v_mul_f32_e32 v98, v88, v247
	v_max_f32_e32 v88, v93, v93
	v_max_f32_e32 v92, v92, v92
	v_max_f32_e32 v88, 0, v88
	v_mul_f32_e32 v93, v89, v247
	v_max_f32_e32 v89, v94, v94
	v_mul_f32_e32 v94, v90, v247
	v_max_f32_e32 v90, v95, v95
	v_max_f32_e32 v91, v91, v91
	v_lshl_add_u64 v[96:97], s[8:9], 0, v[148:149]
	v_max_f32_e32 v92, 0, v92
	v_mul_f32_e32 v88, v88, v88
	v_max_f32_e32 v89, 0, v89
	v_max_f32_e32 v90, 0, v90
	v_max_f32_e32 v91, 0, v91
	v_max_f32_e32 v80, v80, v80
	v_lshl_add_u64 v[96:97], v[96:97], 0, s[6:7]
	v_mul_f32_e32 v92, v92, v92
	v_mul_f32_e32 v88, v88, v247
	v_mul_f32_e32 v89, v89, v89
	v_mul_f32_e32 v90, v90, v90
	v_mul_f32_e32 v91, v91, v91
	v_max_f32_e32 v80, 0, v80
	v_max_f32_e32 v81, v81, v81
	v_max_f32_e32 v82, v82, v82
	v_lshl_add_u64 v[96:97], v[96:97], 0, v[140:141]
	v_mul_f32_e32 v92, v92, v247
	v_mul_f32_e32 v89, v89, v247
	v_mul_f32_e32 v90, v90, v247
	v_mul_f32_e32 v91, v91, v247
	v_cvt_pk_bf16_f32 v88, v92, v88
	v_mul_f32_e32 v80, v80, v80
	v_max_f32_e32 v81, 0, v81
	v_max_f32_e32 v82, 0, v82
	v_cvt_pk_bf16_f32 v89, v89, v90
	v_cvt_pk_bf16_f32 v90, v98, v93
	v_cvt_pk_bf16_f32 v91, v94, v91
	global_store_dwordx4 v[96:97], v[88:91], off
	v_max_f32_e32 v84, v84, v84
	v_mul_f32_e32 v81, v81, v81
	v_mul_f32_e32 v88, v80, v247
	v_max_f32_e32 v80, v85, v85
	v_mul_f32_e32 v82, v82, v82
	v_max_f32_e32 v84, 0, v84
	v_max_f32_e32 v80, 0, v80
	v_mul_f32_e32 v85, v81, v247
	v_max_f32_e32 v81, v86, v86
	v_mul_f32_e32 v86, v82, v247
	v_max_f32_e32 v82, v87, v87
	v_mul_f32_e32 v84, v84, v84
	v_mul_f32_e32 v80, v80, v80
	v_max_f32_e32 v81, 0, v81
	v_max_f32_e32 v82, 0, v82
	v_max_f32_e32 v83, v83, v83
	v_mul_f32_e32 v84, v84, v247
	v_mul_f32_e32 v80, v80, v247
	v_mul_f32_e32 v81, v81, v81
	v_max_f32_e32 v83, 0, v83
	v_mul_f32_e32 v82, v82, v82
	v_max_f32_e32 v72, v72, v72
	v_mul_f32_e32 v81, v81, v247
	v_mul_f32_e32 v82, v82, v247
	v_mul_f32_e32 v83, v83, v83
	v_cvt_pk_bf16_f32 v80, v84, v80
	v_add_co_u32_e32 v84, vcc, s49, v96
	v_max_f32_e32 v72, 0, v72
	v_max_f32_e32 v73, v73, v73
	v_max_f32_e32 v74, v74, v74
	v_mul_f32_e32 v83, v83, v247
	v_cvt_pk_bf16_f32 v81, v81, v82
	v_cvt_pk_bf16_f32 v82, v88, v85
	v_addc_co_u32_e32 v85, vcc, 0, v97, vcc
	v_mul_f32_e32 v72, v72, v72
	v_max_f32_e32 v73, 0, v73
	v_max_f32_e32 v74, 0, v74
	v_cvt_pk_bf16_f32 v83, v86, v83
	global_store_dwordx4 v[84:85], v[80:83], off
	v_mul_f32_e32 v73, v73, v73
	v_mul_f32_e32 v74, v74, v74
	v_mul_f32_e32 v82, v72, v248
	v_max_f32_e32 v72, v77, v77
	v_max_f32_e32 v76, v76, v76
	v_max_f32_e32 v72, 0, v72
	v_mul_f32_e32 v77, v73, v248
	v_max_f32_e32 v73, v78, v78
	v_mul_f32_e32 v78, v74, v248
	v_max_f32_e32 v74, v79, v79
	v_max_f32_e32 v75, v75, v75
	v_lshl_add_u64 v[80:81], s[8:9], 0, v[150:151]
	v_max_f32_e32 v76, 0, v76
	v_mul_f32_e32 v72, v72, v72
	v_max_f32_e32 v73, 0, v73
	v_max_f32_e32 v74, 0, v74
	v_max_f32_e32 v75, 0, v75
	v_max_f32_e32 v64, v64, v64
	v_lshl_add_u64 v[80:81], v[80:81], 0, s[6:7]
	v_mul_f32_e32 v76, v76, v76
	v_mul_f32_e32 v72, v72, v248
	v_mul_f32_e32 v73, v73, v73
	v_mul_f32_e32 v74, v74, v74
	v_mul_f32_e32 v75, v75, v75
	v_max_f32_e32 v64, 0, v64
	v_max_f32_e32 v65, v65, v65
	v_max_f32_e32 v66, v66, v66
	v_lshl_add_u64 v[80:81], v[80:81], 0, v[140:141]
	v_mul_f32_e32 v76, v76, v248
	v_mul_f32_e32 v73, v73, v248
	v_mul_f32_e32 v74, v74, v248
	v_mul_f32_e32 v75, v75, v248
	v_cvt_pk_bf16_f32 v72, v76, v72
	v_mul_f32_e32 v64, v64, v64
	v_max_f32_e32 v65, 0, v65
	v_max_f32_e32 v66, 0, v66
	v_cvt_pk_bf16_f32 v73, v73, v74
	v_cvt_pk_bf16_f32 v74, v82, v77
	v_cvt_pk_bf16_f32 v75, v78, v75
	global_store_dwordx4 v[80:81], v[72:75], off
	v_max_f32_e32 v68, v68, v68
	v_mul_f32_e32 v65, v65, v65
	v_mul_f32_e32 v72, v64, v248
	v_max_f32_e32 v64, v69, v69
	v_mul_f32_e32 v66, v66, v66
	v_max_f32_e32 v68, 0, v68
	v_max_f32_e32 v64, 0, v64
	v_mul_f32_e32 v69, v65, v248
	v_max_f32_e32 v65, v70, v70
	v_mul_f32_e32 v70, v66, v248
	v_max_f32_e32 v66, v71, v71
	v_mul_f32_e32 v68, v68, v68
	v_mul_f32_e32 v64, v64, v64
	v_max_f32_e32 v65, 0, v65
	v_max_f32_e32 v66, 0, v66
	v_max_f32_e32 v67, v67, v67
	v_mul_f32_e32 v68, v68, v248
	v_mul_f32_e32 v64, v64, v248
	v_mul_f32_e32 v65, v65, v65
	v_max_f32_e32 v67, 0, v67
	v_mul_f32_e32 v66, v66, v66
	v_max_f32_e32 v56, v56, v56
	v_mul_f32_e32 v65, v65, v248
	v_mul_f32_e32 v66, v66, v248
	v_mul_f32_e32 v67, v67, v67
	v_cvt_pk_bf16_f32 v64, v68, v64
	v_add_co_u32_e32 v68, vcc, s49, v80
	v_max_f32_e32 v56, 0, v56
	v_max_f32_e32 v57, v57, v57
	v_max_f32_e32 v58, v58, v58
	v_mul_f32_e32 v67, v67, v248
	v_cvt_pk_bf16_f32 v65, v65, v66
	v_cvt_pk_bf16_f32 v66, v72, v69
	v_addc_co_u32_e32 v69, vcc, 0, v81, vcc
	v_mul_f32_e32 v56, v56, v56
	v_max_f32_e32 v57, 0, v57
	v_max_f32_e32 v58, 0, v58
	v_cvt_pk_bf16_f32 v67, v70, v67
	global_store_dwordx4 v[68:69], v[64:67], off
	v_mul_f32_e32 v57, v57, v57
	v_mul_f32_e32 v58, v58, v58
	v_mul_f32_e32 v66, v56, v249
	v_max_f32_e32 v56, v61, v61
	v_max_f32_e32 v60, v60, v60
	v_max_f32_e32 v56, 0, v56
	v_mul_f32_e32 v61, v57, v249
	v_max_f32_e32 v57, v62, v62
	v_mul_f32_e32 v62, v58, v249
	v_max_f32_e32 v58, v63, v63
	v_max_f32_e32 v59, v59, v59
	v_lshl_add_u64 v[64:65], s[8:9], 0, v[152:153]
	v_max_f32_e32 v60, 0, v60
	v_mul_f32_e32 v56, v56, v56
	v_max_f32_e32 v57, 0, v57
	v_max_f32_e32 v58, 0, v58
	v_max_f32_e32 v59, 0, v59
	v_max_f32_e32 v48, v48, v48
	v_lshl_add_u64 v[64:65], v[64:65], 0, s[6:7]
	v_mul_f32_e32 v60, v60, v60
	v_mul_f32_e32 v56, v56, v249
	v_mul_f32_e32 v57, v57, v57
	v_mul_f32_e32 v58, v58, v58
	v_mul_f32_e32 v59, v59, v59
	v_max_f32_e32 v48, 0, v48
	v_max_f32_e32 v49, v49, v49
	v_max_f32_e32 v50, v50, v50
; __device__ __forceinline__ unsigned cvt_pk_bf16(float lo, float hi) { unsigned r; asm volatile("v_cvt_pk_bf16_f32 %0, %1, %2" : "=v"(r) : "v"(lo), "v"(hi)); return r; }
;     __device__ __forceinline__ void operator()(const f32x4 (&acc)[2][2][4][2], const Unit& u, int wr, int wc, int fr, int fq) const {
;     ...
;             for (int m = 0; m < 4; ++m) { const int row = row0 + ai * HALF + m * 16; const float rr = r2[ai][m];
;                 bf16_t* rowp = O + ((size_t)u.pm * (ldc / 64) * 256 + (size_t)(row - u.pm * BM)) * 64 + (size_t)(col0 >> 6) * (256 * 64) + (col0 & 63);
; #pragma unroll
;                 for (int bj = 0; bj < 2; ++bj) { f32x4 v0 = acc[ai][bj][m][0], v1 = acc[ai][bj][m][1];
; #pragma unroll
;                     for (int e = 0; e < 4; ++e) { const float a = fmaxf(v0[e], 0.f), b = fmaxf(v1[e], 0.f); v0[e] = a * a * rr; v1[e] = b * b * rr; }
;                     u32x4 w; w.x = cvt_pk_bf16(v0[0], v0[1]); w.y = cvt_pk_bf16(v0[2], v0[3]); w.z = cvt_pk_bf16(v1[0], v1[1]); w.w = cvt_pk_bf16(v1[2], v1[3]);
;                     *(u32x4*)(rowp + (size_t)bj * (2 * 256 * 64)) = w; } }
	v_lshl_add_u64 v[64:65], v[64:65], 0, v[140:141]
	v_mul_f32_e32 v60, v60, v249
	v_mul_f32_e32 v57, v57, v249
	v_mul_f32_e32 v58, v58, v249
	v_mul_f32_e32 v59, v59, v249
	v_cvt_pk_bf16_f32 v56, v60, v56
	v_mul_f32_e32 v48, v48, v48
	v_max_f32_e32 v49, 0, v49
	v_max_f32_e32 v50, 0, v50
	v_cvt_pk_bf16_f32 v57, v57, v58
	v_cvt_pk_bf16_f32 v58, v66, v61
	v_cvt_pk_bf16_f32 v59, v62, v59
	global_store_dwordx4 v[64:65], v[56:59], off
	v_max_f32_e32 v52, v52, v52
	v_mul_f32_e32 v49, v49, v49
	v_mul_f32_e32 v56, v48, v249
	v_max_f32_e32 v48, v53, v53
	v_mul_f32_e32 v50, v50, v50
	v_max_f32_e32 v52, 0, v52
	v_max_f32_e32 v48, 0, v48
	v_mul_f32_e32 v53, v49, v249
	v_max_f32_e32 v49, v54, v54
	v_mul_f32_e32 v54, v50, v249
	v_max_f32_e32 v50, v55, v55
	v_mul_f32_e32 v52, v52, v52
	v_mul_f32_e32 v48, v48, v48
	v_max_f32_e32 v49, 0, v49
	v_max_f32_e32 v50, 0, v50
	v_max_f32_e32 v51, v51, v51
	v_mul_f32_e32 v52, v52, v249
	v_mul_f32_e32 v48, v48, v249
	v_mul_f32_e32 v49, v49, v49
	v_max_f32_e32 v51, 0, v51
	v_mul_f32_e32 v50, v50, v50
	v_max_f32_e32 v40, v40, v40
	v_mul_f32_e32 v49, v49, v249
	v_mul_f32_e32 v50, v50, v249
	v_mul_f32_e32 v51, v51, v51
	v_cvt_pk_bf16_f32 v48, v52, v48
	v_add_co_u32_e32 v52, vcc, s49, v64
	v_max_f32_e32 v40, 0, v40
	v_max_f32_e32 v41, v41, v41
	v_max_f32_e32 v42, v42, v42
	v_mul_f32_e32 v51, v51, v249
	v_cvt_pk_bf16_f32 v49, v49, v50
	v_cvt_pk_bf16_f32 v50, v56, v53
	v_addc_co_u32_e32 v53, vcc, 0, v65, vcc
	v_mul_f32_e32 v40, v40, v40
	v_max_f32_e32 v41, 0, v41
	v_max_f32_e32 v42, 0, v42
	v_cvt_pk_bf16_f32 v51, v54, v51
	global_store_dwordx4 v[52:53], v[48:51], off
	v_mul_f32_e32 v41, v41, v41
	v_mul_f32_e32 v42, v42, v42
	v_mul_f32_e32 v50, v40, v250
	v_max_f32_e32 v40, v45, v45
	v_max_f32_e32 v44, v44, v44
	v_max_f32_e32 v40, 0, v40
	v_mul_f32_e32 v45, v41, v250
	v_max_f32_e32 v41, v46, v46
	v_mul_f32_e32 v46, v42, v250
	v_max_f32_e32 v42, v47, v47
	v_max_f32_e32 v43, v43, v43
	v_lshl_add_u64 v[48:49], s[8:9], 0, v[154:155]
	v_max_f32_e32 v44, 0, v44
	v_mul_f32_e32 v40, v40, v40
	v_max_f32_e32 v41, 0, v41
	v_max_f32_e32 v42, 0, v42
	v_max_f32_e32 v43, 0, v43
	v_max_f32_e32 v32, v32, v32
	v_lshl_add_u64 v[48:49], v[48:49], 0, s[6:7]
	v_mul_f32_e32 v44, v44, v44
	v_mul_f32_e32 v40, v40, v250
	v_mul_f32_e32 v41, v41, v41
	v_mul_f32_e32 v42, v42, v42
	v_mul_f32_e32 v43, v43, v43
	v_max_f32_e32 v32, 0, v32
	v_max_f32_e32 v33, v33, v33
	v_max_f32_e32 v34, v34, v34
	v_lshl_add_u64 v[48:49], v[48:49], 0, v[140:141]
	v_mul_f32_e32 v44, v44, v250
	v_mul_f32_e32 v41, v41, v250
	v_mul_f32_e32 v42, v42, v250
	v_mul_f32_e32 v43, v43, v250
	v_cvt_pk_bf16_f32 v40, v44, v40
	v_mul_f32_e32 v32, v32, v32
	v_max_f32_e32 v33, 0, v33
	v_max_f32_e32 v34, 0, v34
	v_cvt_pk_bf16_f32 v41, v41, v42
	v_cvt_pk_bf16_f32 v42, v50, v45
	v_cvt_pk_bf16_f32 v43, v46, v43
	global_store_dwordx4 v[48:49], v[40:43], off
	v_max_f32_e32 v36, v36, v36
	v_mul_f32_e32 v33, v33, v33
	v_mul_f32_e32 v40, v32, v250
	v_max_f32_e32 v32, v37, v37
	v_mul_f32_e32 v34, v34, v34
	v_max_f32_e32 v36, 0, v36
	v_max_f32_e32 v32, 0, v32
	v_mul_f32_e32 v37, v33, v250
	v_max_f32_e32 v33, v38, v38
	v_mul_f32_e32 v38, v34, v250
	v_max_f32_e32 v34, v39, v39
	v_mul_f32_e32 v36, v36, v36
	v_mul_f32_e32 v32, v32, v32
	v_max_f32_e32 v33, 0, v33
	v_max_f32_e32 v34, 0, v34
	v_max_f32_e32 v35, v35, v35
	v_mul_f32_e32 v36, v36, v250
	v_mul_f32_e32 v32, v32, v250
	v_mul_f32_e32 v33, v33, v33
	v_max_f32_e32 v35, 0, v35
	v_mul_f32_e32 v34, v34, v34
	v_max_f32_e32 v24, v24, v24
	v_mul_f32_e32 v33, v33, v250
	v_mul_f32_e32 v34, v34, v250
	v_mul_f32_e32 v35, v35, v35
	v_cvt_pk_bf16_f32 v32, v36, v32
	v_add_co_u32_e32 v36, vcc, s49, v48
	v_max_f32_e32 v24, 0, v24
	v_max_f32_e32 v25, v25, v25
	v_max_f32_e32 v26, v26, v26
	v_mul_f32_e32 v35, v35, v250
	v_cvt_pk_bf16_f32 v33, v33, v34
	v_cvt_pk_bf16_f32 v34, v40, v37
	v_addc_co_u32_e32 v37, vcc, 0, v49, vcc
	v_mul_f32_e32 v24, v24, v24
	v_max_f32_e32 v25, 0, v25
	v_max_f32_e32 v26, 0, v26
	v_cvt_pk_bf16_f32 v35, v38, v35
	global_store_dwordx4 v[36:37], v[32:35], off
	v_mul_f32_e32 v25, v25, v25
	v_mul_f32_e32 v26, v26, v26
	v_mul_f32_e32 v34, v24, v251
	v_max_f32_e32 v24, v29, v29
	v_max_f32_e32 v28, v28, v28
	v_max_f32_e32 v24, 0, v24
	v_mul_f32_e32 v29, v25, v251
	v_max_f32_e32 v25, v30, v30
	v_mul_f32_e32 v30, v26, v251
	v_max_f32_e32 v26, v31, v31
	v_max_f32_e32 v27, v27, v27
; __device__ __forceinline__ unsigned cvt_pk_bf16(float lo, float hi) { unsigned r; asm volatile("v_cvt_pk_bf16_f32 %0, %1, %2" : "=v"(r) : "v"(lo), "v"(hi)); return r; }
; #define PG8_BAR __builtin_amdgcn_s_barrier()
;     __device__ __forceinline__ void operator()(const f32x4 (&acc)[2][2][4][2], const Unit& u, int wr, int wc, int fr, int fq) const {
;     ...
;             for (int m = 0; m < 4; ++m) { const int row = row0 + ai * HALF + m * 16; const float rr = r2[ai][m];
;                 bf16_t* rowp = O + ((size_t)u.pm * (ldc / 64) * 256 + (size_t)(row - u.pm * BM)) * 64 + (size_t)(col0 >> 6) * (256 * 64) + (col0 & 63);
; #pragma unroll
;                 for (int bj = 0; bj < 2; ++bj) { f32x4 v0 = acc[ai][bj][m][0], v1 = acc[ai][bj][m][1];
; #pragma unroll
;                     for (int e = 0; e < 4; ++e) { const float a = fmaxf(v0[e], 0.f), b = fmaxf(v1[e], 0.f); v0[e] = a * a * rr; v1[e] = b * b * rr; }
;                     u32x4 w; w.x = cvt_pk_bf16(v0[0], v0[1]); w.y = cvt_pk_bf16(v0[2], v0[3]); w.z = cvt_pk_bf16(v1[0], v1[1]); w.w = cvt_pk_bf16(v1[2], v1[3]);
;                     *(u32x4*)(rowp + (size_t)bj * (2 * 256 * 64)) = w; } }
; template <class Epi, class Sched, bool ALIGN_EPI = false, bool SP2 = false, bool ABLK = false>
; __device__ __forceinline__ void gemm_phase(PG8_LAS unsigned char* lds, const Gemm g, const Sched& S, const Epi& E) {
;     ...
;         if (!has_next) break;
; #pragma unroll
;         for (int a = 0; a < 2; ++a)
; #pragma unroll
;             for (int b = 0; b < 2; ++b)
; #pragma unroll
;                 for (int m = 0; m < 4; ++m)
; #pragma unroll
;                     for (int n = 0; n < 2; ++n) acc[a][b][m][n] = (f32x4){0.f, 0.f, 0.f, 0.f};
;         cur = nxt; cA = nA; cB = nB; ++ui;
;         if constexpr (ALIGN_EPI) { if (wr == 1) PG8_BAR; }
	v_lshl_add_u64 v[32:33], s[8:9], 0, v[156:157]
	v_max_f32_e32 v28, 0, v28
	v_mul_f32_e32 v24, v24, v24
	v_max_f32_e32 v25, 0, v25
	v_max_f32_e32 v26, 0, v26
	v_max_f32_e32 v27, 0, v27
	v_max_f32_e32 v16, v16, v16
	v_lshl_add_u64 v[32:33], v[32:33], 0, s[6:7]
	v_mul_f32_e32 v28, v28, v28
	v_mul_f32_e32 v24, v24, v251
	v_mul_f32_e32 v25, v25, v25
	v_mul_f32_e32 v26, v26, v26
	v_mul_f32_e32 v27, v27, v27
	v_max_f32_e32 v16, 0, v16
	v_max_f32_e32 v17, v17, v17
	v_max_f32_e32 v18, v18, v18
	v_lshl_add_u64 v[32:33], v[32:33], 0, v[140:141]
	v_mul_f32_e32 v28, v28, v251
	v_mul_f32_e32 v25, v25, v251
	v_mul_f32_e32 v26, v26, v251
	v_mul_f32_e32 v27, v27, v251
	v_cvt_pk_bf16_f32 v24, v28, v24
	v_mul_f32_e32 v16, v16, v16
	v_max_f32_e32 v17, 0, v17
	v_max_f32_e32 v18, 0, v18
	v_cvt_pk_bf16_f32 v25, v25, v26
	v_cvt_pk_bf16_f32 v26, v34, v29
	v_cvt_pk_bf16_f32 v27, v30, v27
	global_store_dwordx4 v[32:33], v[24:27], off
	v_max_f32_e32 v20, v20, v20
	v_mul_f32_e32 v17, v17, v17
	v_mul_f32_e32 v24, v16, v251
	v_max_f32_e32 v16, v21, v21
	v_mul_f32_e32 v18, v18, v18
	v_max_f32_e32 v20, 0, v20
	v_max_f32_e32 v16, 0, v16
	v_mul_f32_e32 v21, v17, v251
	v_max_f32_e32 v17, v22, v22
	v_mul_f32_e32 v22, v18, v251
	v_max_f32_e32 v18, v23, v23
	v_mul_f32_e32 v20, v20, v20
	v_mul_f32_e32 v16, v16, v16
	v_max_f32_e32 v17, 0, v17
	v_max_f32_e32 v18, 0, v18
	v_max_f32_e32 v19, v19, v19
	v_mul_f32_e32 v20, v20, v251
	v_mul_f32_e32 v16, v16, v251
	v_mul_f32_e32 v17, v17, v17
	v_max_f32_e32 v19, 0, v19
	v_mul_f32_e32 v18, v18, v18
	v_max_f32_e32 v8, v8, v8
	v_mul_f32_e32 v17, v17, v251
	v_mul_f32_e32 v18, v18, v251
	v_mul_f32_e32 v19, v19, v19
	v_cvt_pk_bf16_f32 v16, v20, v16
	v_add_co_u32_e32 v20, vcc, s49, v32
	v_max_f32_e32 v8, 0, v8
	v_max_f32_e32 v9, v9, v9
	v_max_f32_e32 v10, v10, v10
	v_mul_f32_e32 v19, v19, v251
	v_cvt_pk_bf16_f32 v17, v17, v18
	v_cvt_pk_bf16_f32 v18, v24, v21
	v_addc_co_u32_e32 v21, vcc, 0, v33, vcc
	v_mul_f32_e32 v8, v8, v8
	v_max_f32_e32 v9, 0, v9
	v_max_f32_e32 v10, 0, v10
	v_cvt_pk_bf16_f32 v19, v22, v19
	global_store_dwordx4 v[20:21], v[16:19], off
	v_mul_f32_e32 v9, v9, v9
	v_mul_f32_e32 v10, v10, v10
	v_mul_f32_e32 v18, v8, v252
	v_max_f32_e32 v8, v13, v13
	v_max_f32_e32 v12, v12, v12
	v_max_f32_e32 v8, 0, v8
	v_mul_f32_e32 v13, v9, v252
	v_max_f32_e32 v9, v14, v14
	v_mul_f32_e32 v14, v10, v252
	v_max_f32_e32 v10, v15, v15
	v_max_f32_e32 v11, v11, v11
	v_lshl_add_u64 v[16:17], s[8:9], 0, v[158:159]
	v_max_f32_e32 v12, 0, v12
	v_mul_f32_e32 v8, v8, v8
	v_max_f32_e32 v9, 0, v9
	v_max_f32_e32 v10, 0, v10
	v_max_f32_e32 v11, 0, v11
	v_max_f32_e32 v0, v0, v0
	v_lshl_add_u64 v[16:17], v[16:17], 0, s[6:7]
	v_mul_f32_e32 v12, v12, v12
	v_mul_f32_e32 v8, v8, v252
	v_mul_f32_e32 v9, v9, v9
	v_mul_f32_e32 v10, v10, v10
	v_mul_f32_e32 v11, v11, v11
	v_max_f32_e32 v0, 0, v0
	v_max_f32_e32 v1, v1, v1
	v_max_f32_e32 v2, v2, v2
	v_lshl_add_u64 v[16:17], v[16:17], 0, v[140:141]
	v_mul_f32_e32 v12, v12, v252
	v_mul_f32_e32 v9, v9, v252
	v_mul_f32_e32 v10, v10, v252
	v_mul_f32_e32 v11, v11, v252
	v_cvt_pk_bf16_f32 v8, v12, v8
	v_mul_f32_e32 v0, v0, v0
	v_max_f32_e32 v1, 0, v1
	v_max_f32_e32 v2, 0, v2
	v_cvt_pk_bf16_f32 v9, v9, v10
	v_cvt_pk_bf16_f32 v10, v18, v13
	v_cvt_pk_bf16_f32 v11, v14, v11
	global_store_dwordx4 v[16:17], v[8:11], off
	v_max_f32_e32 v4, v4, v4
	v_mul_f32_e32 v1, v1, v1
	v_mul_f32_e32 v8, v0, v252
	v_max_f32_e32 v0, v5, v5
	v_mul_f32_e32 v2, v2, v2
	v_max_f32_e32 v4, 0, v4
	v_max_f32_e32 v0, 0, v0
	v_mul_f32_e32 v5, v1, v252
	v_max_f32_e32 v1, v6, v6
	v_mul_f32_e32 v6, v2, v252
	v_max_f32_e32 v2, v7, v7
	v_mul_f32_e32 v4, v4, v4
	v_mul_f32_e32 v0, v0, v0
	v_max_f32_e32 v1, 0, v1
	v_max_f32_e32 v2, 0, v2
	v_mul_f32_e32 v4, v4, v252
	v_mul_f32_e32 v0, v0, v252
	v_mul_f32_e32 v1, v1, v1
	v_max_f32_e32 v3, v3, v3
	v_mul_f32_e32 v2, v2, v2
	v_mul_f32_e32 v1, v1, v252
	v_max_f32_e32 v3, 0, v3
	v_mul_f32_e32 v2, v2, v252
	v_cvt_pk_bf16_f32 v0, v4, v0
	v_add_co_u32_e32 v4, vcc, 0x10000, v16
	v_mul_f32_e32 v3, v3, v3
	v_cvt_pk_bf16_f32 v1, v1, v2
	v_cvt_pk_bf16_f32 v2, v8, v5
	s_nop 0
	v_addc_co_u32_e32 v5, vcc, 0, v17, vcc
	v_mul_f32_e32 v3, v3, v252
	s_andn2_b64 vcc, exec, s[26:27]
	s_mov_b64 s[6:7], -1
	v_cvt_pk_bf16_f32 v3, v6, v3
	global_store_dwordx4 v[4:5], v[0:3], off
	s_cbranch_vccnz .LBB0_530
	s_andn2_b64 vcc, exec, s[14:15]
	s_cbranch_vccnz .LBB0_529
	s_barrier
	s_branch .LBB0_529

; __global__ void __launch_bounds__(NWAVES * 64, 2) hymba_fwd(Args args) {
	.amdhsa_kernel _Z9hymba_fwd4Args
		.amdhsa_group_segment_fixed_size 0
		.amdhsa_private_segment_fixed_size 0
		.amdhsa_kernarg_size 384
		.amdhsa_user_sgpr_count 2
		.amdhsa_user_sgpr_dispatch_ptr 0
		.amdhsa_user_sgpr_queue_ptr 0
		.amdhsa_user_sgpr_kernarg_segment_ptr 1
		.amdhsa_user_sgpr_dispatch_id 0
		.amdhsa_user_sgpr_kernarg_preload_length 0
		.amdhsa_user_sgpr_kernarg_preload_offset 0
		.amdhsa_user_sgpr_private_segment_size 0
		.amdhsa_uses_dynamic_stack 0
		.amdhsa_enable_private_segment 0
		.amdhsa_system_sgpr_workgroup_id_x 1
		.amdhsa_system_sgpr_workgroup_id_y 0
		.amdhsa_system_sgpr_workgroup_id_z 0
		.amdhsa_system_sgpr_workgroup_info 0
		.amdhsa_system_vgpr_workitem_id 2
		.amdhsa_next_free_vgpr 253
		.amdhsa_next_free_sgpr 102
		.amdhsa_accum_offset 256
		.amdhsa_reserve_vcc 1
		.amdhsa_float_round_mode_32 0
		.amdhsa_float_round_mode_16_64 0
		.amdhsa_float_denorm_mode_32 3
		.amdhsa_float_denorm_mode_16_64 3
		.amdhsa_dx10_clamp 1
		.amdhsa_ieee_mode 1
		.amdhsa_fp16_overflow 0
		.amdhsa_tg_split 0
		.amdhsa_exception_fp_ieee_invalid_op 0
		.amdhsa_exception_fp_denorm_src 0
		.amdhsa_exception_fp_ieee_div_zero 0
		.amdhsa_exception_fp_ieee_overflow 0
		.amdhsa_exception_fp_ieee_underflow 0
		.amdhsa_exception_fp_ieee_inexact 0
		.amdhsa_exception_int_div_zero 0
	.end_amdhsa_kernel

; __global__ void __launch_bounds__(NWAVES * 64, 2) hymba_fwd(Args args) {
amdhsa.kernels:
  - .agpr_count:     0
    .args:
      - .offset:         0
        .size:           128
        .value_kind:     by_value
      - .offset:         128
        .size:           4
        .value_kind:     hidden_block_count_x
      - .offset:         132
        .size:           4
        .value_kind:     hidden_block_count_y
      - .offset:         136
        .size:           4
        .value_kind:     hidden_block_count_z
      - .offset:         140
        .size:           2
        .value_kind:     hidden_group_size_x
      - .offset:         142
        .size:           2
        .value_kind:     hidden_group_size_y
      - .offset:         144
        .size:           2
        .value_kind:     hidden_group_size_z
      - .offset:         146
        .size:           2
        .value_kind:     hidden_remainder_x
      - .offset:         148
        .size:           2
        .value_kind:     hidden_remainder_y
      - .offset:         150
        .size:           2
        .value_kind:     hidden_remainder_z
      - .offset:         168
        .size:           8
        .value_kind:     hidden_global_offset_x
      - .offset:         176
        .size:           8
        .value_kind:     hidden_global_offset_y
      - .offset:         184
        .size:           8
        .value_kind:     hidden_global_offset_z
      - .offset:         192
        .size:           2
        .value_kind:     hidden_grid_dims
      - .offset:         216
        .size:           8
        .value_kind:     hidden_multigrid_sync_arg
      - .offset:         248
        .size:           4
        .value_kind:     hidden_dynamic_lds_size
    .group_segment_fixed_size: 0
    .kernarg_segment_align: 8
    .kernarg_segment_size: 384
    .language:       OpenCL C
    .language_version:
      - 2
      - 0
    .max_flat_workgroup_size: 512
    .name:           _Z9hymba_fwd4Args
    .private_segment_fixed_size: 0
    .sgpr_count:     108
    .sgpr_spill_count: 36
    .symbol:         _Z9hymba_fwd4Args.kd
    .uniform_work_group_size: 1
    .uses_dynamic_stack: false
    .vgpr_count:     253
    .vgpr_spill_count: 0
    .wavefront_size: 64
